# v31 plus: HGRN H1 state-increment tile computed transposed (MFMA operands swapped) so each lane holds 8 consecutive k after a permlane32 swap; 32 global_store_short per wave become 4 global_store_dwor
# baseline (speedup 1.0000x reference)
.LBB0_236:
	ds_read_b128 v[16:19], v54 offset:53248
	ds_read_b128 v[0:3], v55 offset:34816
	ds_read_b128 v[66:69], v54 offset:53280
	ds_read_b128 v[20:23], v55 offset:34848
	ds_read_b128 v[70:73], v54 offset:53312
	ds_read_b128 v[24:27], v55 offset:34880
	ds_read_b128 v[74:77], v54 offset:53344
	ds_read_b128 v[28:31], v55 offset:34912
	s_waitcnt lgkmcnt(6)
	v_mfma_f32_32x32x16_bf16 v[0:15], v[0:3], v[16:19], 0
	s_waitcnt lgkmcnt(4)
	v_mfma_f32_32x32x16_bf16 v[0:15], v[20:23], v[66:69], v[0:15]
	s_waitcnt lgkmcnt(2)
	v_mfma_f32_32x32x16_bf16 v[0:15], v[24:27], v[70:73], v[0:15]
	s_waitcnt lgkmcnt(0)
	v_mfma_f32_32x32x16_bf16 v[0:15], v[28:31], v[74:77], v[0:15]
	ds_read_b128 v[20:23], v56 offset:34816
	ds_read_b128 v[78:81], v56 offset:34848
	ds_read_b128 v[82:85], v56 offset:34880
	ds_read_b128 v[86:89], v56 offset:34912
	v_readlane_b32 s2, v254, 4
	s_add_i32 s16, s16, s2
	v_readlane_b32 s2, v254, 3
	s_add_i32 s11, s11, s2
	s_waitcnt lgkmcnt(3)
	v_mfma_f32_32x32x16_bf16 v[16:31], v[20:23], v[16:19], 0
	s_waitcnt lgkmcnt(2)
	v_mfma_f32_32x32x16_bf16 v[16:31], v[78:81], v[66:69], v[16:31]
	s_waitcnt lgkmcnt(1)
	v_mfma_f32_32x32x16_bf16 v[16:31], v[82:85], v[70:73], v[16:31]
	s_waitcnt lgkmcnt(0)
	v_mfma_f32_32x32x16_bf16 v[16:31], v[86:89], v[74:77], v[16:31]
	v_and_b32_e32 v88, 31, v218
	v_lshrrev_b32_e32 v87, 7, v218
	v_lshl_add_u32 v88, v87, 5, v88
	v_lshlrev_b32_e32 v88, 8, v88
	v_bfe_u32 v87, v218, 6, 1
	v_lshl_add_u32 v88, v87, 7, v88
	v_lshlrev_b32_e32 v65, 8, v87
	v_bfe_u32 v87, v218, 5, 1
	v_lshl_add_u32 v88, v87, 4, v88
	v_lshl_add_u32 v65, v87, 4, v65
	v_add_u32_e32 v65, 0x1b000, v65
	v_mov_b32_e32 v89, 0
	v_lshl_add_u64 v[88:89], s[6:7], 0, v[88:89]
	ds_read_b128 v[66:69], v65
	ds_read_b128 v[70:73], v65 offset:32
	ds_read_b128 v[74:77], v65 offset:64
	ds_read_b128 v[78:81], v65 offset:96
	ds_read_b128 v[82:85], v65 offset:128
	s_waitcnt lgkmcnt(0)
	v_mul_f32_e32 v0, v0, v66
	v_mul_f32_e32 v1, v1, v67
	v_mul_f32_e32 v2, v2, v68
	v_mul_f32_e32 v3, v3, v69
	v_mul_f32_e32 v4, v4, v70
	v_mul_f32_e32 v5, v5, v71
	v_mul_f32_e32 v6, v6, v72
	v_mul_f32_e32 v7, v7, v73
	v_mul_f32_e32 v8, v8, v74
	v_mul_f32_e32 v9, v9, v75
	v_mul_f32_e32 v10, v10, v76
	v_mul_f32_e32 v11, v11, v77
	v_mul_f32_e32 v12, v12, v78
	v_mul_f32_e32 v13, v13, v79
	v_mul_f32_e32 v14, v14, v80
	v_mul_f32_e32 v15, v15, v81
	ds_read_b128 v[66:69], v65 offset:160
	ds_read_b128 v[70:73], v65 offset:192
	ds_read_b128 v[74:77], v65 offset:224
	v_cvt_pk_bf16_f32 v0, v0, v1
	v_cvt_pk_bf16_f32 v1, v2, v3
	v_cvt_pk_bf16_f32 v2, v4, v5
	v_cvt_pk_bf16_f32 v3, v6, v7
	v_cvt_pk_bf16_f32 v4, v8, v9
	v_cvt_pk_bf16_f32 v5, v10, v11
	v_cvt_pk_bf16_f32 v6, v12, v13
	v_cvt_pk_bf16_f32 v7, v14, v15
	s_nop 1
	v_permlane32_swap_b32_e32 v0, v2
	v_permlane32_swap_b32_e32 v1, v3
	v_permlane32_swap_b32_e32 v4, v6
	v_permlane32_swap_b32_e32 v5, v7
	global_store_dwordx4 v[88:89], v[0:3], off
	global_store_dwordx4 v[88:89], v[4:7], off offset:32
	s_waitcnt lgkmcnt(0)
	v_mul_f32_e32 v16, v16, v82
	v_mul_f32_e32 v17, v17, v83
	v_mul_f32_e32 v18, v18, v84
	v_mul_f32_e32 v19, v19, v85
	v_mul_f32_e32 v20, v20, v66
	v_mul_f32_e32 v21, v21, v67
	v_mul_f32_e32 v22, v22, v68
	v_mul_f32_e32 v23, v23, v69
	v_mul_f32_e32 v24, v24, v70
	v_mul_f32_e32 v25, v25, v71
	v_mul_f32_e32 v26, v26, v72
	v_mul_f32_e32 v27, v27, v73
	v_mul_f32_e32 v28, v28, v74
	v_mul_f32_e32 v29, v29, v75
	v_mul_f32_e32 v30, v30, v76
	v_mul_f32_e32 v31, v31, v77
	v_cvt_pk_bf16_f32 v16, v16, v17
	v_cvt_pk_bf16_f32 v17, v18, v19
	v_cvt_pk_bf16_f32 v18, v20, v21
	v_cvt_pk_bf16_f32 v19, v22, v23
	v_cvt_pk_bf16_f32 v20, v24, v25
	v_cvt_pk_bf16_f32 v21, v26, v27
	v_cvt_pk_bf16_f32 v22, v28, v29
	v_cvt_pk_bf16_f32 v23, v30, v31
	s_nop 1
	v_permlane32_swap_b32_e32 v16, v18
	v_permlane32_swap_b32_e32 v17, v19
	v_permlane32_swap_b32_e32 v20, v22
	v_permlane32_swap_b32_e32 v21, v23
	global_store_dwordx4 v[88:89], v[16:19], off offset:64
	global_store_dwordx4 v[88:89], v[20:23], off offset:96
	v_readlane_b32 s2, v254, 20
	v_readlane_b32 s3, v254, 21
	s_nop 1
	v_lshl_add_u64 v[36:37], v[36:37], 0, s[2:3]
	s_nop 1
	v_readlane_b32 s2, v254, 10
	v_readlane_b32 s3, v254, 11
	s_add_u32 s6, s6, s2
	s_addc_u32 s7, s7, s3
	s_and_b64 vcc, exec, s[8:9]
	s_barrier
	s_cbranch_vccnz .LBB0_241
